# attention row-max reduction via v_permlane16/32_swap instead of two dependent ds_bpermute round trips
# baseline (speedup 1.0000x reference)
; DEV float shfl_xor_l(float v, int m, int lane) { return __int_as_float(__builtin_amdgcn_ds_bpermute((lane ^ m) << 2, __float_as_int(v))); }
; DEV float shfl_l(float v, int srclane) { return __int_as_float(__builtin_amdgcn_ds_bpermute(srclane << 2, __float_as_int(v))); }
; DEV float ex2(float x) { return __builtin_amdgcn_exp2f(x); }
; DEV void attn_item(const Params& p, int layer, int h, int qb, float lam, bf16_t* lds) {
;     ...
;     float al[2];
; #pragma unroll
;     for (int i = 0; i < 2; i++) {
;       float mx = -1e30f;
; #pragma unroll
;       for (int j = 0; j < 8; j++)
; #pragma unroll
;         for (int r = 0; r < 4; r++) mx = fmaxf(mx, s[i][j][r]);
;       mx = fmaxf(mx, shfl_xor_l(mx, 16, lane));
;       mx = fmaxf(mx, shfl_xor_l(mx, 32, lane));
;       const float mold = i == 0 ? mrun0 : mrun1;
;       const float mnew = (mx > mold + 8.f) ? mx : mold;
;       al[i] = ex2(mold - mnew);
;       float ps = 0.f;
; #pragma unroll
;       for (int j = 0; j < 8; j++)
; #pragma unroll
;         for (int r = 0; r < 4; r++) { const float pv = ex2(s[i][j][r] - mnew); s[i][j][r] = pv; ps += pv; }
;       if (i == 0) { mrun0 = mnew; lrun0 = lrun0 * al[0] + ps; } else { mrun1 = mnew; lrun1 = lrun1 * al[1] + ps; }
;     }
;     if (__builtin_amdgcn_ballot_w64(al[0] != 1.f || al[1] != 1.f) != 0ull) {
; #pragma unroll
;       for (int i = 0; i < 2; i++) {
;         float ao[4];
; #pragma unroll
;         for (int r = 0; r < 4; r++) ao[r] = shfl_l(al[i], lg * 4 + r);
; #pragma unroll
;         for (int je = 0; je < 8; je++)
; #pragma unroll
;           for (int r = 0; r < 4; r++) o[i][je][r] *= ao[r];
;       }
;     }
.LBB0_710:
	v_max3_f32 v0, v176, s68, v177
	v_max3_f32 v0, v0, v178, v179
	v_max3_f32 v2, v168, s68, v169
	v_max3_f32 v0, v0, v172, v173
	v_max3_f32 v2, v2, v170, v171
	v_max3_f32 v0, v0, v174, v175
	v_max3_f32 v2, v2, v164, v165
	v_max3_f32 v0, v0, v160, v161
	v_max3_f32 v2, v2, v166, v167
	v_max3_f32 v0, v0, v162, v163
	v_max3_f32 v2, v2, v152, v153
	v_max3_f32 v0, v0, v156, v157
	v_max3_f32 v2, v2, v154, v155
	v_max3_f32 v0, v0, v158, v159
	v_max3_f32 v2, v2, v148, v149
	v_max3_f32 v0, v0, v144, v145
	v_max3_f32 v2, v2, v150, v151
	v_max3_f32 v0, v0, v146, v147
	v_max3_f32 v2, v2, v136, v137
	v_max3_f32 v0, v0, v140, v141
	v_max3_f32 v2, v2, v138, v139
	v_max3_f32 v0, v0, v142, v143
	v_max3_f32 v2, v2, v132, v133
	v_max3_f32 v0, v0, v128, v129
	v_max3_f32 v2, v2, v134, v135
	v_max3_f32 v0, v0, v130, v131
	v_max3_f32 v2, v2, v120, v121
	v_max3_f32 v0, v0, v124, v125
	v_max3_f32 v2, v2, v122, v123
	v_max3_f32 v0, v0, v126, v127
	v_max3_f32 v2, v2, v116, v117
	v_max3_f32 v194, v2, v118, v119
	v_mov_b32_e32 v3, v0
	v_mov_b32_e32 v195, v0
	v_mov_b32_e32 v196, v194
	v_mov_b32_e32 v197, v194
	s_nop 1
	v_permlane16_swap_b32_e32 v3, v195
	v_permlane16_swap_b32_e32 v196, v197
	v_max_f32_e32 v0, v3, v195
	v_max_f32_e32 v194, v196, v197
	v_mov_b32_e32 v3, v0
	v_mov_b32_e32 v195, v0
	v_mov_b32_e32 v196, v194
	v_mov_b32_e32 v197, v194
	s_nop 1
	v_permlane32_swap_b32_e32 v3, v195
	v_permlane32_swap_b32_e32 v196, v197
	v_max_f32_e32 v0, v3, v195
	v_max_f32_e32 v196, v196, v197
	v_mov_b32_e32 v2, v192
	v_mov_b32_e32 v3, v193
	s_mov_b32 s0, 0x41000000
	v_pk_add_f32 v[194:195], v[2:3], s[0:1] op_sel_hi:[1,0]
	v_cmp_gt_f32_e32 vcc, v0, v195
	s_nop 1
	v_cndmask_b32_e32 v193, v193, v0, vcc
	v_cmp_gt_f32_e32 vcc, v196, v194
	s_nop 1
	v_cndmask_b32_e32 v192, v192, v196, vcc
	v_pk_add_f32 v[2:3], v[2:3], v[192:193] neg_lo:[0,1] neg_hi:[0,1]
	s_nop 0
	v_exp_f32_e32 v3, v3
	v_exp_f32_e32 v2, v2
	v_cmp_neq_f32_e32 vcc, 1.0, v3
	v_cmp_neq_f32_e64 s[0:1], 1.0, v2
	s_or_b64 vcc, s[0:1], vcc
	s_cbranch_vccz .LBB0_707
	ds_bpermute_b32 v194, v182, v3
	ds_bpermute_b32 v195, v227, v3
	ds_bpermute_b32 v196, v189, v3
	ds_bpermute_b32 v197, v187, v3
	s_waitcnt lgkmcnt(2)
	v_pk_mul_f32 v[100:101], v[100:101], v[194:195]
	v_pk_mul_f32 v[96:97], v[96:97], v[194:195]
	s_waitcnt lgkmcnt(0)
	v_pk_mul_f32 v[102:103], v[102:103], v[196:197]
	v_pk_mul_f32 v[98:99], v[98:99], v[196:197]
	v_pk_mul_f32 v[114:115], v[114:115], v[196:197]
	v_pk_mul_f32 v[112:113], v[112:113], v[194:195]
	v_pk_mul_f32 v[94:95], v[94:95], v[196:197]
	v_pk_mul_f32 v[92:93], v[92:93], v[194:195]
	v_pk_mul_f32 v[110:111], v[110:111], v[196:197]
	v_pk_mul_f32 v[108:109], v[108:109], v[194:195]
	v_pk_mul_f32 v[90:91], v[90:91], v[196:197]
	v_pk_mul_f32 v[88:89], v[88:89], v[194:195]
	v_pk_mul_f32 v[106:107], v[106:107], v[196:197]
	v_pk_mul_f32 v[104:105], v[104:105], v[194:195]
	v_pk_mul_f32 v[86:87], v[86:87], v[196:197]
	v_pk_mul_f32 v[84:85], v[84:85], v[194:195]
	ds_bpermute_b32 v194, v182, v2
	ds_bpermute_b32 v195, v227, v2
	ds_bpermute_b32 v196, v189, v2
	ds_bpermute_b32 v197, v187, v2
	s_waitcnt lgkmcnt(2)
	v_pk_mul_f32 v[80:81], v[80:81], v[194:195]
	v_pk_mul_f32 v[76:77], v[76:77], v[194:195]
	s_waitcnt lgkmcnt(0)
	v_pk_mul_f32 v[82:83], v[82:83], v[196:197]
	v_pk_mul_f32 v[78:79], v[78:79], v[196:197]
	v_pk_mul_f32 v[74:75], v[74:75], v[196:197]
	v_pk_mul_f32 v[72:73], v[72:73], v[194:195]
	v_pk_mul_f32 v[70:71], v[70:71], v[196:197]
	v_pk_mul_f32 v[68:69], v[68:69], v[194:195]
	v_pk_mul_f32 v[66:67], v[66:67], v[196:197]
	v_pk_mul_f32 v[64:65], v[64:65], v[194:195]
	v_pk_mul_f32 v[62:63], v[62:63], v[196:197]
	v_pk_mul_f32 v[60:61], v[60:61], v[194:195]
	v_pk_mul_f32 v[58:59], v[58:59], v[196:197]
	v_pk_mul_f32 v[56:57], v[56:57], v[194:195]
	v_pk_mul_f32 v[54:55], v[54:55], v[196:197]
	v_pk_mul_f32 v[52:53], v[52:53], v[194:195]
	s_branch .LBB0_707
